# v62 plus lane^16/lane^32 reduction hops via v_permlane16/32_swap (fused-LN stats, attention row max, rms)
# baseline (speedup 1.0000x reference)
; #define LAS __attribute__((address_space(3)))
; __device__ __forceinline__ float shx(float v, int mask, int lane) { return __int_as_float(__builtin_amdgcn_ds_bpermute((lane ^ mask) << 2, __float_as_int(v))); }
; __device__ __forceinline__ void attn_dif_unit(LAS unsigned char* lds, const int tid, const int wave_s, const bf16_t* q, const bf16_t* k0, const bf16_t* k1, const bf16_t* vt0, const bf16_t* vt1, ...
;     ...
;             {
;                 bf16x8 qf[4], kfa[4], kfb[4];
; #pragma unroll
;                 for (int ks = 0; ks < 4; ++ks) qf[ks] = *(const LAS bf16x8*)(qb + c32 * DA_KP + m * 128 + ks * 32 + hi * 16);
; #pragma unroll
;                 for (int ks = 0; ks < 4; ++ks) kfa[ks] = *(const LAS bf16x8*)(kb + c32 * DA_KP + m * 128 + ks * 32 + hi * 16);
; #pragma unroll
;                 for (int ks = 0; ks < 4; ++ks) kfb[ks] = *(const LAS bf16x8*)(kb + (32 + c32) * DA_KP + m * 128 + ks * 32 + hi * 16);
; #pragma unroll
;                 for (int r = 0; r < 16; ++r) { sacc[0][r] = nm; sacc[1][r] = nm; }
; #pragma unroll
;                 for (int ks = 0; ks < 4; ++ks) sacc[0] = __builtin_amdgcn_mfma_f32_32x32x16_bf16(kfa[ks], qf[ks], sacc[0], 0, 0, 0);
; #pragma unroll
;                 for (int ks = 0; ks < 4; ++ks) sacc[1] = __builtin_amdgcn_mfma_f32_32x32x16_bf16(kfb[ks], qf[ks], sacc[1], 0, 0, 0);
;             }
;             float mx = fmaxf(sacc[0][0], sacc[1][0]);
; #pragma unroll
;             for (int a = 0; a < 2; ++a)
; #pragma unroll
;                 for (int r = 1; r < 16; r += 2) mx = fmaxf(fmaxf(mx, sacc[a][r]), sacc[a][r + 1 < 16 ? r + 1 : r]);
;             mx = fmaxf(mx, shx(mx, 32, lane));
.Ldif_noload:
.LBB0_989:
	v_mul_u32_u24_e32 v0, 0x110, v208
	v_add_u32_e32 v0, s22, v0
	v_add_u32_e32 v252, v0, v213
	ds_read_b128 v[2:5], v215
	ds_read_b128 v[6:9], v252
	v_xor_b32_e32 v144, 0x80000000, v218
	v_mov_b32_e32 v145, v144
	v_mov_b64_e32 v[146:147], v[144:145]
	v_mov_b64_e32 v[148:149], v[144:145]
	v_mov_b64_e32 v[150:151], v[144:145]
	v_mov_b64_e32 v[152:153], v[144:145]
	v_mov_b64_e32 v[154:155], v[144:145]
	v_mov_b64_e32 v[156:157], v[144:145]
	v_mov_b64_e32 v[158:159], v[144:145]
	s_cmp_eq_u32 s55, 1
	s_cselect_b64 s[6:7], -1, 0
	s_waitcnt lgkmcnt(0)
	v_mfma_f32_32x32x16_bf16 v[160:175], v[6:9], v[2:5], v[144:159]
	ds_read_b128 v[6:9], v252 offset:32
	ds_read_b128 v[10:13], v215 offset:32
	s_cmp_lg_u32 s55, 1
	s_cselect_b64 s[10:11], -1, 0
	s_and_b64 vcc, exec, s[10:11]
	s_waitcnt lgkmcnt(0)
	v_mfma_f32_32x32x16_bf16 v[160:175], v[6:9], v[10:13], v[160:175]
	ds_read_b128 v[6:9], v252 offset:64
	ds_read_b128 v[192:195], v215 offset:64
	s_waitcnt lgkmcnt(0)
	v_mfma_f32_32x32x16_bf16 v[160:175], v[6:9], v[192:195], v[160:175]
	ds_read_b128 v[6:9], v252 offset:8704
	s_waitcnt lgkmcnt(0)
	v_mfma_f32_32x32x16_bf16 v[144:159], v[6:9], v[2:5], v[144:159]
	ds_read_b128 v[2:5], v252 offset:8736
	s_waitcnt lgkmcnt(0)
	v_mfma_f32_32x32x16_bf16 v[144:159], v[2:5], v[10:13], v[144:159]
	ds_read_b128 v[2:5], v252 offset:8768
	s_waitcnt lgkmcnt(0)
	v_mfma_f32_32x32x16_bf16 v[144:159], v[2:5], v[192:195], v[144:159]
	ds_read_b128 v[2:5], v252 offset:8800
	ds_read_b128 v[6:9], v215 offset:96
	s_waitcnt lgkmcnt(0)
	v_mfma_f32_32x32x16_bf16 v[144:159], v[2:5], v[6:9], v[144:159]
	ds_read_b128 v[2:5], v252 offset:96
	s_waitcnt lgkmcnt(0)
	v_mfma_f32_32x32x16_bf16 v[160:175], v[2:5], v[6:9], v[160:175]
	s_nop 8
	v_max_f32_e32 v0, v144, v144
	s_nop 1
	v_max_f32_e32 v2, v160, v160
	v_max_f32_e32 v0, v2, v0
	v_max3_f32 v0, v0, v161, v162
	v_max3_f32 v0, v0, v163, v164
	v_max3_f32 v0, v0, v165, v166
	v_max3_f32 v0, v0, v167, v168
	v_max3_f32 v0, v0, v169, v170
	v_max3_f32 v0, v0, v171, v172
	v_max3_f32 v0, v0, v173, v174
	v_max3_f32 v0, v0, v175, v145
	v_max3_f32 v0, v0, v146, v147
	v_max3_f32 v0, v0, v148, v149
	v_max3_f32 v0, v0, v150, v151
	v_max3_f32 v0, v0, v152, v153
	v_max3_f32 v0, v0, v154, v155
	v_max3_f32 v0, v0, v156, v157
	v_max3_f32 v0, v0, v158, v159
	v_mov_b32_e32 v2, v0
	s_nop 1
	v_permlane32_swap_b32_e32 v2, v0
	v_max_f32_e32 v192, v0, v2
	s_cbranch_vccz .LBB0_993
	v_cmp_lt_f32_e32 vcc, s64, v192
	s_mov_b64 s[14:15], 0
	s_mov_b64 s[12:13], 0
	s_cbranch_vccz .LBB0_992
	v_max_f32_e32 v0, v192, v192
	v_max_f32_e32 v0, 0, v0
	s_mov_b64 s[12:13], -1

; __device__ __forceinline__ void attn_dif_unit(LAS unsigned char* lds, const int tid, const int wave_s, const bf16_t* q, const bf16_t* k0, const bf16_t* k1, const bf16_t* vt0, const bf16_t* vt1, ...
;     ...
;             {
;                 bf16x8 qf[4], kfa[4], kfb[4];
; #pragma unroll
;                 for (int ks = 0; ks < 4; ++ks) qf[ks] = *(const LAS bf16x8*)(qb + c32 * DA_KP + m * 128 + ks * 32 + hi * 16);
; #pragma unroll
;                 for (int ks = 0; ks < 4; ++ks) kfa[ks] = *(const LAS bf16x8*)(kb + c32 * DA_KP + m * 128 + ks * 32 + hi * 16);
; #pragma unroll
;                 for (int ks = 0; ks < 4; ++ks) kfb[ks] = *(const LAS bf16x8*)(kb + (32 + c32) * DA_KP + m * 128 + ks * 32 + hi * 16);
; #pragma unroll
;                 for (int r = 0; r < 16; ++r) { sacc[0][r] = nm; sacc[1][r] = nm; }
; #pragma unroll
;                 for (int ks = 0; ks < 4; ++ks) sacc[0] = __builtin_amdgcn_mfma_f32_32x32x16_bf16(kfa[ks], qf[ks], sacc[0], 0, 0, 0);
; #pragma unroll
;                 for (int ks = 0; ks < 4; ++ks) sacc[1] = __builtin_amdgcn_mfma_f32_32x32x16_bf16(kfb[ks], qf[ks], sacc[1], 0, 0, 0);
;             }
;             float mx = fmaxf(sacc[0][0], sacc[1][0]);
; #pragma unroll
;             for (int a = 0; a < 2; ++a)
; #pragma unroll
;                 for (int r = 1; r < 16; r += 2) mx = fmaxf(fmaxf(mx, sacc[a][r]), sacc[a][r + 1 < 16 ? r + 1 : r]);
;     ...
;             for (int a = 0; a < 2; ++a)
; #pragma unroll
;                 for (int r = 0; r < 16; ++r) { const float p = ex2(sacc[a][r]); sacc[a][r] = p; ls += p; }
;             l_run[m] += ls;
;             bf16x8 pf[4];
; #pragma unroll
;             for (int a = 0; a < 2; ++a)
; #pragma unroll
;                 for (int jj = 0; jj < 2; ++jj) { u32x4 wv; wv.x = cvt_pk_bf16(sacc[a][8 * jj + 0], sacc[a][8 * jj + 1]); wv.y = cvt_pk_bf16(sacc[a][8 * jj + 2], sacc[a][8 * jj + 3]);
;                     wv.z = cvt_pk_bf16(sacc[a][8 * jj + 4], sacc[a][8 * jj + 5]); wv.w = cvt_pk_bf16(sacc[a][8 * jj + 6], sacc[a][8 * jj + 7]); pf[2 * a + jj] = __builtin_bit_cast(bf16x8, wv); }
;             if (m == 1 && t + 1 < ntile) DA_LOAD(t + 1);
;             {
;                 const LAS unsigned char* vp0 = vb + c32 * DA_VP + hi * 16;
;     ...
;                 bf16x8 va[4], vc[4];
;                 DA_VF(va, 0); DA_VF(vc, 1); DA_PV(va, 0); DA_VF(va, 2); DA_PV(vc, 1); DA_VF(vc, 3); DA_PV(va, 2); DA_PV(vc, 3);
.LBB0_997:
	v_mul_u32_u24_e32 v0, 0x90, v208
	v_add_u32_e32 v0, s22, v0
	v_add_u32_e32 v220, v0, v213
	v_exp_f32_e32 v221, v160
	v_exp_f32_e32 v222, v161
	v_exp_f32_e32 v223, v162
	v_exp_f32_e32 v224, v163
	v_exp_f32_e32 v225, v164
	v_exp_f32_e32 v226, v165
	v_exp_f32_e32 v227, v166
	v_exp_f32_e32 v228, v167
	v_exp_f32_e32 v229, v168
	v_exp_f32_e32 v230, v169
	v_exp_f32_e32 v231, v170
	v_exp_f32_e32 v232, v171
	v_exp_f32_e32 v233, v172
	v_exp_f32_e32 v234, v173
	v_exp_f32_e32 v235, v174
	v_exp_f32_e32 v236, v175
	v_exp_f32_e32 v237, v144
	v_exp_f32_e32 v238, v145
	v_exp_f32_e32 v239, v146
	v_exp_f32_e32 v247, v147
	v_exp_f32_e32 v241, v148
	v_exp_f32_e32 v243, v149
	v_exp_f32_e32 v240, v150
	v_exp_f32_e32 v192, v151
	v_exp_f32_e32 v193, v152
	v_exp_f32_e32 v194, v153
	v_exp_f32_e32 v195, v154
	v_exp_f32_e32 v196, v155
	v_exp_f32_e32 v197, v156
	v_exp_f32_e32 v242, v157
	v_exp_f32_e32 v250, v158
	v_exp_f32_e32 v251, v159
	ds_read_b128 v[148:151], v220 offset:17408
	ds_read_b128 v[152:155], v220 offset:17440
	ds_read_b128 v[156:159], v220 offset:17472
	ds_read_b128 v[160:163], v220 offset:17504
	ds_read_b128 v[164:167], v220 offset:22016
	ds_read_b128 v[168:171], v220 offset:22048
	v_cvt_pk_bf16_f32 v2, v221, v222
	v_cvt_pk_bf16_f32 v3, v223, v224
	v_cvt_pk_bf16_f32 v4, v225, v226
	v_cvt_pk_bf16_f32 v5, v227, v228
	v_cvt_pk_bf16_f32 v6, v229, v230
	v_cvt_pk_bf16_f32 v7, v231, v232
	v_cvt_pk_bf16_f32 v8, v233, v234
	v_cvt_pk_bf16_f32 v9, v235, v236
	v_cvt_pk_bf16_f32 v10, v237, v238
	v_cvt_pk_bf16_f32 v11, v239, v247
	v_cvt_pk_bf16_f32 v12, v241, v243
	v_cvt_pk_bf16_f32 v13, v240, v192
	v_cvt_pk_bf16_f32 v144, v193, v194
	v_cvt_pk_bf16_f32 v145, v195, v196
	v_cvt_pk_bf16_f32 v146, v197, v242
	v_cvt_pk_bf16_f32 v147, v250, v251
	s_waitcnt lgkmcnt(5)
	v_mfma_f32_32x32x16_bf16 v[128:143], v[148:151], v[2:5], v[128:143]
	ds_read_b128 v[172:175], v220 offset:22080
	s_waitcnt lgkmcnt(5)
	v_mfma_f32_32x32x16_bf16 v[128:143], v[152:155], v[6:9], v[128:143]
	ds_read_b128 v[148:151], v220 offset:22112
	s_waitcnt lgkmcnt(5)
	v_mfma_f32_32x32x16_bf16 v[128:143], v[156:159], v[10:13], v[128:143]
	ds_read_b128 v[152:155], v220 offset:26624
	s_waitcnt lgkmcnt(5)
	v_mfma_f32_32x32x16_bf16 v[128:143], v[160:163], v[144:147], v[128:143]
	ds_read_b128 v[156:159], v220 offset:26656
	s_waitcnt lgkmcnt(5)
	v_mfma_f32_32x32x16_bf16 v[96:111], v[164:167], v[2:5], v[96:111]
	ds_read_b128 v[160:163], v220 offset:26688
	s_waitcnt lgkmcnt(5)
	v_mfma_f32_32x32x16_bf16 v[96:111], v[168:171], v[6:9], v[96:111]
	ds_read_b128 v[164:167], v220 offset:26720
	s_waitcnt lgkmcnt(5)
	v_mfma_f32_32x32x16_bf16 v[96:111], v[172:175], v[10:13], v[96:111]
	ds_read_b128 v[168:171], v220 offset:31232
	s_waitcnt lgkmcnt(5)
	v_mfma_f32_32x32x16_bf16 v[96:111], v[148:151], v[144:147], v[96:111]
	ds_read_b128 v[172:175], v220 offset:31264
	s_waitcnt lgkmcnt(5)
	v_mfma_f32_32x32x16_bf16 v[64:79], v[152:155], v[2:5], v[64:79]
	ds_read_b128 v[148:151], v220 offset:31296
	s_waitcnt lgkmcnt(5)
	v_mfma_f32_32x32x16_bf16 v[64:79], v[156:159], v[6:9], v[64:79]
	ds_read_b128 v[152:155], v220 offset:31328
	s_waitcnt lgkmcnt(5)
	v_mfma_f32_32x32x16_bf16 v[64:79], v[160:163], v[10:13], v[64:79]
	s_waitcnt lgkmcnt(4)
	v_mfma_f32_32x32x16_bf16 v[64:79], v[164:167], v[144:147], v[64:79]
	s_waitcnt lgkmcnt(3)
	v_mfma_f32_32x32x16_bf16 v[32:47], v[168:171], v[2:5], v[32:47]
	s_waitcnt lgkmcnt(2)
	v_mfma_f32_32x32x16_bf16 v[32:47], v[172:175], v[6:9], v[32:47]
	s_waitcnt lgkmcnt(1)
	v_mfma_f32_32x32x16_bf16 v[32:47], v[148:151], v[10:13], v[32:47]
	s_waitcnt lgkmcnt(0)
	v_mfma_f32_32x32x16_bf16 v[32:47], v[152:155], v[144:147], v[32:47]
	ds_read_b128 v[2:5], v215 offset:128
	ds_read_b128 v[6:9], v252 offset:128
	v_xor_b32_e32 v144, 0x80000000, v217
	v_mov_b32_e32 v145, v144
	v_mov_b64_e32 v[146:147], v[144:145]
	v_mov_b64_e32 v[148:149], v[144:145]
	v_mov_b64_e32 v[150:151], v[144:145]
	v_mov_b64_e32 v[152:153], v[144:145]
	v_mov_b64_e32 v[154:155], v[144:145]
	v_mov_b64_e32 v[156:157], v[144:145]
	v_mov_b64_e32 v[158:159], v[144:145]
	s_and_b64 vcc, exec, s[10:11]
	s_waitcnt lgkmcnt(0)
	v_mfma_f32_32x32x16_bf16 v[160:175], v[6:9], v[2:5], v[144:159]
	ds_read_b128 v[6:9], v252 offset:160
	ds_read_b128 v[10:13], v215 offset:160
	s_waitcnt lgkmcnt(0)
	v_mfma_f32_32x32x16_bf16 v[160:175], v[6:9], v[10:13], v[160:175]
	ds_read_b128 v[6:9], v252 offset:192
	ds_read_b128 v[204:207], v215 offset:192
	s_waitcnt lgkmcnt(0)
	v_mfma_f32_32x32x16_bf16 v[160:175], v[6:9], v[204:207], v[160:175]
	ds_read_b128 v[6:9], v252 offset:8832
	s_waitcnt lgkmcnt(0)
	v_mfma_f32_32x32x16_bf16 v[144:159], v[6:9], v[2:5], v[144:159]
	ds_read_b128 v[2:5], v252 offset:8864
	s_waitcnt lgkmcnt(0)
	v_mfma_f32_32x32x16_bf16 v[144:159], v[2:5], v[10:13], v[144:159]
	ds_read_b128 v[2:5], v252 offset:8896
	s_waitcnt lgkmcnt(0)
	v_mfma_f32_32x32x16_bf16 v[144:159], v[2:5], v[204:207], v[144:159]
	ds_read_b128 v[2:5], v252 offset:8928
	ds_read_b128 v[6:9], v215 offset:224
	s_waitcnt lgkmcnt(0)
	v_mfma_f32_32x32x16_bf16 v[144:159], v[2:5], v[6:9], v[144:159]
	ds_read_b128 v[2:5], v252 offset:224
	s_waitcnt lgkmcnt(0)
	v_mfma_f32_32x32x16_bf16 v[160:175], v[2:5], v[6:9], v[160:175]
	s_nop 8
	v_max_f32_e32 v0, v144, v144
	s_nop 1
	v_max_f32_e32 v2, v160, v160
	v_max_f32_e32 v0, v2, v0
	v_max3_f32 v0, v0, v161, v162
	v_max3_f32 v0, v0, v163, v164
	v_max3_f32 v0, v0, v165, v166
	v_max3_f32 v0, v0, v167, v168
	v_max3_f32 v0, v0, v169, v170
	v_max3_f32 v0, v0, v171, v172
	v_max3_f32 v0, v0, v173, v174
	v_max3_f32 v0, v0, v175, v145
	v_max3_f32 v0, v0, v146, v147
	v_max3_f32 v0, v0, v148, v149
	v_max3_f32 v0, v0, v150, v151
	v_max3_f32 v0, v0, v152, v153
	v_max3_f32 v0, v0, v154, v155
	v_max3_f32 v0, v0, v156, v157
	v_max3_f32 v0, v0, v158, v159
	v_mov_b32_e32 v2, v0
	s_nop 1
	v_permlane32_swap_b32_e32 v2, v0
	v_max_f32_e32 v252, v0, v2
	s_cbranch_vccz .LBB0_1001
	v_cmp_lt_f32_e32 vcc, s64, v252
	s_mov_b64 s[12:13], 0
	s_mov_b64 s[10:11], 0
	s_cbranch_vccz .LBB0_1000
	v_max_f32_e32 v0, v252, v252
	v_max_f32_e32 v0, 0, v0
	s_mov_b64 s[10:11], -1
